# branch-phase staggering reduced from 4 groups to 2 groups (insertion points 2 and 4) now that conv/shift tiles are cheaper
# baseline (speedup 1.0000x reference)
; DEV int ltid() { int t = threadIdx.x; asm volatile("" : "+v"(t)); return t; }
; DEV int vblock() { const int per = gridDim.x >> 3; return (blockIdx.x & 7) * per + (blockIdx.x >> 3); }
; DEV void attn_tile(const Params& p, int l, int tile, char* smem, bool do_store = true) {
;   bf16_t* ZQ = (bf16_t*)(p.ws + O_ZQ);
;   const bf16_t* ZK = (const bf16_t*)(p.ws + O_ZK);
;   const bf16_t* VT = (const bf16_t*)(p.ws + O_VT);
;   int b, head, q0, nkeys, qbase;
;   if (tile < 1024) { b = tile >> 7; head = (tile >> 5) & 3; q0 = (tile & 31) * 128; nkeys = TK; qbase = b * SEQ; }
;   else { const int tt = tile - 1024; b = tt >> 3; head = (tt >> 1) & 3; q0 = (tt & 1) * 128; nkeys = CTXL; qbase = T_LAT + b * CTXL; }
;   const int tid = ltid(), lane = tid & 63, w = tid >> 6, ql = lane & 31, hh = lane >> 5, map = w >> 2, qg = w & 3;
;   const int qrow = qbase + q0 + qg * 32 + ql;
;   const float lam_init = l == 0 ? 0.2f : 0.35550907f;
;   float lam;
;   {
;     const float a1 = p.att_lq1[l * 64 + lane] * p.att_lk1[l * 64 + lane];
;     const float a2 = p.att_lq2[l * 64 + lane] * p.att_lk2[l * 64 + lane];
;     lam = __expf(wsum(a1)) - __expf(wsum(a2)) + lam_init;
;   }
; DEV void branch_phase(const Params& p, int l, char* smem) {
;   const bool last = (l == 1);
;   for (int L = vblock(); L < 1088 + 544 + 1088; L += gridDim.x) {
;     if (L < 1088) { if (!(last && L >= 1024)) attn_tile(p, l, L, smem); }
;     else if (L < 1632) { if (!(last && L - 1088 >= 512)) conv_tile(p, l, L - 1088, smem); }
;     else shift_tile(p, l, L - 1632);
;   }
.LBB0_217:
	s_andn2_b64 vcc, exec, s[0:1]
	s_mov_b64 s[78:79], 0
	s_cbranch_vccnz .LBB0_222
	v_readlane_b32 s58, v255, 44
	s_cmp_gt_i32 s47, 0
	s_mov_b64 s[78:79], -1
	v_readlane_b32 s59, v255, 45
	s_mov_b32 s52, 0x8800
	s_cbranch_scc0 .LBB0_618
	s_cmp_gt_i32 s47, 1
	s_mov_b64 s[0:1], -1
	s_cbranch_scc0 .LBB0_645
	v_writelane_b32 v255, s47, 50
	v_readlane_b32 s0, v252, 15
	v_writelane_b32 v255, s50, 51
	v_readlane_b32 s1, v252, 16
	s_andn2_b64 vcc, exec, s[0:1]
	v_writelane_b32 v255, s51, 52
	s_cbranch_vccnz .LBB0_644
	v_readlane_b32 s0, v255, 51
	v_readlane_b32 s1, v255, 52
	s_mov_b32 s40, s0
	s_mul_hi_i32 s36, s0, 0x5a00
	s_mul_i32 s37, s0, 0x5a00
	s_mul_hi_i32 s38, s0, 0xf800
	s_mul_i32 s39, s0, 0xf800
	s_lshl_b32 s0, s0, 9
	v_readlane_b32 s30, v255, 44
	s_ashr_i32 s1, s0, 31
	s_add_i32 s30, s30, 10
	s_cmp_lt_u32 s30, 23
	v_readlane_b32 s31, v255, 45
	s_cselect_b64 vcc, -1, 0
	s_lshl_b32 s30, s40, 7
	v_readlane_b32 s76, v251, 21
	s_lshl_b32 s96, s40, 6
	s_ashr_i32 s31, s30, 31
	v_readlane_b32 s84, v251, 29
	v_readlane_b32 s56, v254, 58
	v_readlane_b32 s77, v251, 22
	v_readlane_b32 s85, v251, 30
	s_add_u32 s76, s84, s37
	v_readlane_b32 s57, v254, 59
	v_readlane_b32 s58, v254, 60
	v_readlane_b32 s59, v254, 61
	v_readlane_b32 s60, v254, 62
	v_readlane_b32 s61, v254, 63
	v_readlane_b32 s62, v255, 0
	v_readlane_b32 s63, v255, 1
	v_readlane_b32 s64, v255, 2
	v_readlane_b32 s65, v255, 3
	v_readlane_b32 s66, v255, 4
	v_readlane_b32 s67, v255, 5
	s_addc_u32 s77, s85, s36
	s_lshl_b64 s[0:1], s[0:1], 2
	v_readlane_b32 s68, v255, 6
	v_readlane_b32 s69, v255, 7
	v_readlane_b32 s70, v255, 8
	v_readlane_b32 s71, v255, 9
	s_mov_b64 s[56:57], s[60:61]
	s_add_u32 s42, s56, s0
	s_mov_b64 s[58:59], s[62:63]
	s_addc_u32 s43, s57, s1
	s_add_u32 s44, s58, s0
	s_mov_b64 s[60:61], s[64:65]
	s_addc_u32 s45, s59, s1
	s_add_u32 s46, s60, s0
	v_readlane_b32 s80, v251, 25
	s_addc_u32 s47, s61, s1
	s_lshl_b64 s[0:1], s[30:31], 2
	v_readlane_b32 s81, v251, 26
	s_add_u32 s48, s80, s0
	v_mov_b32_e32 v0, 0x3eb60549
	v_mov_b32_e32 v1, 0x3e4ccccd
	s_mov_b64 s[62:63], s[66:67]
	s_mov_b64 s[64:65], s[68:69]
	s_mov_b64 s[66:67], s[70:71]
	s_addc_u32 s49, s81, s1
	v_readlane_b32 s0, v254, 57
	v_cndmask_b32_e32 v188, v0, v1, vcc
	v_readlane_b32 s64, v255, 38
	v_readlane_b32 s68, v255, 36
	v_readlane_b32 s66, v255, 34
	v_readlane_b32 s60, v255, 32
	s_add_u32 s50, s0, s39
	v_readlane_b32 s0, v255, 10
	v_sub_f32_e32 v189, 1.0, v188
	s_mov_b32 s71, 0x8000
	v_readlane_b32 s70, v255, 41
	v_readlane_b32 s65, v255, 39
	v_readlane_b32 s69, v255, 37
	v_readlane_b32 s67, v255, 35
	s_movk_i32 s41, 0x600
	v_readlane_b32 s61, v255, 33
	s_addc_u32 s51, s0, s38
	v_readlane_b32 s97, v254, 50
	v_readlane_b32 s40, v254, 49
	s_nop 3
	s_bfe_u32 s101, s40, 0x10003
	s_lshl_b32 s101, s101, 1
	s_add_i32 s101, s101, 2
	s_cmp_eq_u32 s101, 0
	s_cbranch_scc0 .Lrot_st
	s_lshl_b32 s100, s92, 2
	s_add_i32 s40, s40, s100
	s_lshl_b32 s100, s33, 2
	s_add_i32 s97, s97, s100

; DEV int vblock() { const int per = gridDim.x >> 3; return (blockIdx.x & 7) * per + (blockIdx.x >> 3); }
; DEV void branch_phase(const Params& p, int l, char* smem) {
;     ...
;   for (int L = vblock(); L < 1088 + 544 + 1088; L += gridDim.x) {
;     if (L < 1088) { if (!(last && L >= 1024)) attn_tile(p, l, L, smem); }
;     else if (L < 1632) { if (!(last && L - 1088 >= 512)) conv_tile(p, l, L - 1088, smem); }
;     else shift_tile(p, l, L - 1632);
;   }
.LBB0_305:
	s_lshr_b32 s100, s40, 8
	s_and_b32 s40, s40, 0xff
	s_bfe_u32 s101, s40, 0x10003
	s_lshl_b32 s101, s101, 1
	s_add_i32 s101, s101, 2
	s_cmp_gt_u32 s100, 3
	s_cbranch_scc1 .Lrot_blk
	s_add_i32 s100, s100, 1
	s_cmp_eq_u32 s100, s101
	s_cbranch_scc1 .Lrot_to4
	s_cmp_eq_u32 s100, 4
	s_cbranch_scc1 .LBB0_644
	s_branch .Lrot_set
